# P4/P5/P6 GEMM K-loop heads pinned at 64-byte phase 12 (alignment padding only)
# baseline (speedup 1.0000x reference)
.LBB0_713:
	s_ashr_i32 s19, s18, 31
	s_lshl_b64 s[22:23], s[18:19], 18
	s_add_u32 s22, s52, s22
	s_addc_u32 s23, s53, s23
	s_and_b64 s[0:1], s[0:1], exec
	s_cselect_b32 s19, s23, s29
	s_cselect_b32 s38, s22, s28
	s_add_u32 s39, s28, 0x100
	v_mov_b32_e32 v0, 0
	s_addc_u32 s40, s29, 0
	s_mov_b32 s41, -2
	v_mov_b32_e32 v1, v0
	v_mov_b32_e32 v2, v0
	v_mov_b32_e32 v3, v0
	v_mov_b32_e32 v4, v0
	v_mov_b32_e32 v5, v0
	v_mov_b32_e32 v6, v0
	v_mov_b32_e32 v7, v0
	v_mov_b32_e32 v8, v0
	v_mov_b32_e32 v9, v0
	v_mov_b32_e32 v10, v0
	v_mov_b32_e32 v11, v0
	v_mov_b32_e32 v12, v0
	v_mov_b32_e32 v13, v0
	v_mov_b32_e32 v14, v0
	v_mov_b32_e32 v15, v0
	v_mov_b32_e32 v16, v0
	v_mov_b32_e32 v17, v0
	v_mov_b32_e32 v18, v0
	v_mov_b32_e32 v19, v0
	v_mov_b32_e32 v20, v0
	v_mov_b32_e32 v21, v0
	v_mov_b32_e32 v22, v0
	v_mov_b32_e32 v23, v0
	v_mov_b32_e32 v24, v0
	v_mov_b32_e32 v25, v0
	v_mov_b32_e32 v26, v0
	v_mov_b32_e32 v27, v0
	v_mov_b32_e32 v28, v0
	v_mov_b32_e32 v29, v0
	v_mov_b32_e32 v30, v0
	v_mov_b32_e32 v31, v0
	v_mov_b32_e32 v32, v0
	v_mov_b32_e32 v33, v0
	v_mov_b32_e32 v34, v0
	v_mov_b32_e32 v35, v0
	v_mov_b32_e32 v36, v0
	v_mov_b32_e32 v37, v0
	v_mov_b32_e32 v38, v0
	v_mov_b32_e32 v39, v0
	v_mov_b32_e32 v40, v0
	v_mov_b32_e32 v41, v0
	v_mov_b32_e32 v42, v0
	v_mov_b32_e32 v43, v0
	v_mov_b32_e32 v44, v0
	v_mov_b32_e32 v45, v0
	v_mov_b32_e32 v46, v0
	v_mov_b32_e32 v47, v0
	v_mov_b32_e32 v48, v0
	v_mov_b32_e32 v49, v0
	v_mov_b32_e32 v50, v0
	v_mov_b32_e32 v51, v0
	v_mov_b32_e32 v52, v0
	v_mov_b32_e32 v53, v0
	v_mov_b32_e32 v54, v0
	v_mov_b32_e32 v55, v0
	v_mov_b32_e32 v56, v0
	v_mov_b32_e32 v57, v0
	v_mov_b32_e32 v58, v0
	v_mov_b32_e32 v59, v0
	v_mov_b32_e32 v60, v0
	v_mov_b32_e32 v61, v0
	v_mov_b32_e32 v62, v0
	v_mov_b32_e32 v63, v0
	v_mov_b32_e32 v64, v0
	v_mov_b32_e32 v65, v0
	v_mov_b32_e32 v66, v0
	v_mov_b32_e32 v67, v0
	v_mov_b32_e32 v68, v0
	v_mov_b32_e32 v69, v0
	v_mov_b32_e32 v70, v0
	v_mov_b32_e32 v71, v0
	v_mov_b32_e32 v72, v0
	v_mov_b32_e32 v73, v0
	v_mov_b32_e32 v74, v0
	v_mov_b32_e32 v75, v0
	v_mov_b32_e32 v76, v0
	v_mov_b32_e32 v77, v0
	v_mov_b32_e32 v78, v0
	v_mov_b32_e32 v79, v0
	v_mov_b32_e32 v80, v0
	v_mov_b32_e32 v81, v0
	v_mov_b32_e32 v82, v0
	v_mov_b32_e32 v83, v0
	v_mov_b32_e32 v84, v0
	v_mov_b32_e32 v85, v0
	v_mov_b32_e32 v86, v0
	v_mov_b32_e32 v87, v0
	v_mov_b32_e32 v88, v0
	v_mov_b32_e32 v89, v0
	v_mov_b32_e32 v90, v0
	v_mov_b32_e32 v91, v0
	v_mov_b32_e32 v92, v0
	v_mov_b32_e32 v93, v0
	v_mov_b32_e32 v94, v0
	v_mov_b32_e32 v95, v0
	v_mov_b32_e32 v96, v0
	v_mov_b32_e32 v97, v0
	v_mov_b32_e32 v98, v0
	v_mov_b32_e32 v99, v0
	v_mov_b32_e32 v100, v0
	v_mov_b32_e32 v101, v0
	v_mov_b32_e32 v102, v0
	v_mov_b32_e32 v103, v0
	v_mov_b32_e32 v104, v0
	v_mov_b32_e32 v105, v0
	v_mov_b32_e32 v106, v0
	v_mov_b32_e32 v107, v0
	v_mov_b32_e32 v108, v0
	v_mov_b32_e32 v109, v0
	v_mov_b32_e32 v110, v0
	v_mov_b32_e32 v111, v0
	v_mov_b32_e32 v114, v0
	v_mov_b32_e32 v115, v0
	v_mov_b32_e32 v116, v0
	v_mov_b32_e32 v117, v0
	v_mov_b32_e32 v118, v0
	v_mov_b32_e32 v119, v0
	v_mov_b32_e32 v120, v0
	v_mov_b32_e32 v121, v0
	v_mov_b32_e32 v122, v0
	v_mov_b32_e32 v123, v0
	v_mov_b32_e32 v124, v0
	v_mov_b32_e32 v125, v0
	v_mov_b32_e32 v126, v0
	v_mov_b32_e32 v127, v0
	v_mov_b32_e32 v128, v0
	v_mov_b32_e32 v129, v0
	.p2align 6
	s_nop 0
	s_nop 0
	s_nop 0

.LBB0_736:
	s_ashr_i32 s13, s12, 31
	s_lshl_b64 s[16:17], s[12:13], 18
	s_add_u32 s16, s28, s16
	s_addc_u32 s17, s29, s17
	s_and_b64 s[0:1], s[0:1], exec
	s_cselect_b32 s13, s17, s23
	s_cselect_b32 s38, s16, s22
	s_add_u32 s39, s22, 0x100
	v_mov_b32_e32 v0, 0
	s_addc_u32 s40, s23, 0
	s_mov_b32 s41, -2
	v_mov_b32_e32 v1, v0
	v_mov_b32_e32 v2, v0
	v_mov_b32_e32 v3, v0
	v_mov_b32_e32 v4, v0
	v_mov_b32_e32 v5, v0
	v_mov_b32_e32 v6, v0
	v_mov_b32_e32 v7, v0
	v_mov_b32_e32 v8, v0
	v_mov_b32_e32 v9, v0
	v_mov_b32_e32 v10, v0
	v_mov_b32_e32 v11, v0
	v_mov_b32_e32 v12, v0
	v_mov_b32_e32 v13, v0
	v_mov_b32_e32 v14, v0
	v_mov_b32_e32 v15, v0
	v_mov_b32_e32 v16, v0
	v_mov_b32_e32 v17, v0
	v_mov_b32_e32 v18, v0
	v_mov_b32_e32 v19, v0
	v_mov_b32_e32 v20, v0
	v_mov_b32_e32 v21, v0
	v_mov_b32_e32 v22, v0
	v_mov_b32_e32 v23, v0
	v_mov_b32_e32 v24, v0
	v_mov_b32_e32 v25, v0
	v_mov_b32_e32 v26, v0
	v_mov_b32_e32 v27, v0
	v_mov_b32_e32 v28, v0
	v_mov_b32_e32 v29, v0
	v_mov_b32_e32 v30, v0
	v_mov_b32_e32 v31, v0
	v_mov_b32_e32 v64, v0
	v_mov_b32_e32 v65, v0
	v_mov_b32_e32 v66, v0
	v_mov_b32_e32 v67, v0
	v_mov_b32_e32 v68, v0
	v_mov_b32_e32 v69, v0
	v_mov_b32_e32 v70, v0
	v_mov_b32_e32 v71, v0
	v_mov_b32_e32 v72, v0
	v_mov_b32_e32 v73, v0
	v_mov_b32_e32 v74, v0
	v_mov_b32_e32 v75, v0
	v_mov_b32_e32 v76, v0
	v_mov_b32_e32 v77, v0
	v_mov_b32_e32 v78, v0
	v_mov_b32_e32 v79, v0
	v_mov_b32_e32 v88, v0
	v_mov_b32_e32 v89, v0
	v_mov_b32_e32 v90, v0
	v_mov_b32_e32 v91, v0
	v_mov_b32_e32 v92, v0
	v_mov_b32_e32 v93, v0
	v_mov_b32_e32 v94, v0
	v_mov_b32_e32 v95, v0
	v_mov_b32_e32 v96, v0
	v_mov_b32_e32 v97, v0
	v_mov_b32_e32 v98, v0
	v_mov_b32_e32 v99, v0
	v_mov_b32_e32 v100, v0
	v_mov_b32_e32 v101, v0
	v_mov_b32_e32 v102, v0
	v_mov_b32_e32 v103, v0
	v_mov_b32_e32 v32, v0
	v_mov_b32_e32 v33, v0
	v_mov_b32_e32 v34, v0
	v_mov_b32_e32 v35, v0
	v_mov_b32_e32 v36, v0
	v_mov_b32_e32 v37, v0
	v_mov_b32_e32 v38, v0
	v_mov_b32_e32 v39, v0
	v_mov_b32_e32 v40, v0
	v_mov_b32_e32 v41, v0
	v_mov_b32_e32 v42, v0
	v_mov_b32_e32 v43, v0
	v_mov_b32_e32 v44, v0
	v_mov_b32_e32 v45, v0
	v_mov_b32_e32 v46, v0
	v_mov_b32_e32 v47, v0
	v_mov_b32_e32 v48, v0
	v_mov_b32_e32 v49, v0
	v_mov_b32_e32 v50, v0
	v_mov_b32_e32 v51, v0
	v_mov_b32_e32 v52, v0
	v_mov_b32_e32 v53, v0
	v_mov_b32_e32 v54, v0
	v_mov_b32_e32 v55, v0
	v_mov_b32_e32 v56, v0
	v_mov_b32_e32 v57, v0
	v_mov_b32_e32 v58, v0
	v_mov_b32_e32 v59, v0
	v_mov_b32_e32 v60, v0
	v_mov_b32_e32 v61, v0
	v_mov_b32_e32 v62, v0
	v_mov_b32_e32 v63, v0
	v_mov_b32_e32 v104, v0
	v_mov_b32_e32 v105, v0
	v_mov_b32_e32 v106, v0
	v_mov_b32_e32 v107, v0
	v_mov_b32_e32 v108, v0
	v_mov_b32_e32 v109, v0
	v_mov_b32_e32 v110, v0
	v_mov_b32_e32 v111, v0
	v_mov_b32_e32 v114, v0
	v_mov_b32_e32 v115, v0
	v_mov_b32_e32 v116, v0
	v_mov_b32_e32 v117, v0
	v_mov_b32_e32 v118, v0
	v_mov_b32_e32 v119, v0
	v_mov_b32_e32 v120, v0
	v_mov_b32_e32 v121, v0
	v_mov_b32_e32 v122, v0
	v_mov_b32_e32 v123, v0
	v_mov_b32_e32 v124, v0
	v_mov_b32_e32 v125, v0
	v_mov_b32_e32 v126, v0
	v_mov_b32_e32 v127, v0
	v_mov_b32_e32 v128, v0
	v_mov_b32_e32 v129, v0
	v_mov_b32_e32 v130, v0
	v_mov_b32_e32 v131, v0
	v_mov_b32_e32 v132, v0
	v_mov_b32_e32 v133, v0
	v_mov_b32_e32 v134, v0
	v_mov_b32_e32 v135, v0
	v_mov_b32_e32 v136, v0
	v_mov_b32_e32 v137, v0
	.p2align 6
	s_nop 0
	s_nop 0
	s_nop 0

.LBB0_798:
	s_ashr_i32 s15, s14, 31
	s_lshl_b64 s[18:19], s[14:15], 18
	s_add_u32 s18, s34, s18
	s_addc_u32 s19, s35, s19
	s_and_b64 s[0:1], s[0:1], exec
	s_cselect_b32 s15, s19, s25
	s_cselect_b32 s38, s18, s24
	s_add_u32 s39, s24, 0x100
	v_mov_b32_e32 v0, 0
	s_addc_u32 s40, s25, 0
	s_mov_b32 s41, -2
	v_mov_b32_e32 v1, v0
	v_mov_b32_e32 v2, v0
	v_mov_b32_e32 v3, v0
	v_mov_b32_e32 v4, v0
	v_mov_b32_e32 v5, v0
	v_mov_b32_e32 v6, v0
	v_mov_b32_e32 v7, v0
	v_mov_b32_e32 v8, v0
	v_mov_b32_e32 v9, v0
	v_mov_b32_e32 v10, v0
	v_mov_b32_e32 v11, v0
	v_mov_b32_e32 v12, v0
	v_mov_b32_e32 v13, v0
	v_mov_b32_e32 v14, v0
	v_mov_b32_e32 v15, v0
	v_mov_b32_e32 v16, v0
	v_mov_b32_e32 v17, v0
	v_mov_b32_e32 v18, v0
	v_mov_b32_e32 v19, v0
	v_mov_b32_e32 v20, v0
	v_mov_b32_e32 v21, v0
	v_mov_b32_e32 v22, v0
	v_mov_b32_e32 v23, v0
	v_mov_b32_e32 v24, v0
	v_mov_b32_e32 v25, v0
	v_mov_b32_e32 v26, v0
	v_mov_b32_e32 v27, v0
	v_mov_b32_e32 v28, v0
	v_mov_b32_e32 v29, v0
	v_mov_b32_e32 v30, v0
	v_mov_b32_e32 v31, v0
	v_mov_b32_e32 v32, v0
	v_mov_b32_e32 v33, v0
	v_mov_b32_e32 v34, v0
	v_mov_b32_e32 v35, v0
	v_mov_b32_e32 v36, v0
	v_mov_b32_e32 v37, v0
	v_mov_b32_e32 v38, v0
	v_mov_b32_e32 v39, v0
	v_mov_b32_e32 v40, v0
	v_mov_b32_e32 v41, v0
	v_mov_b32_e32 v42, v0
	v_mov_b32_e32 v43, v0
	v_mov_b32_e32 v44, v0
	v_mov_b32_e32 v45, v0
	v_mov_b32_e32 v46, v0
	v_mov_b32_e32 v47, v0
	v_mov_b32_e32 v48, v0
	v_mov_b32_e32 v49, v0
	v_mov_b32_e32 v50, v0
	v_mov_b32_e32 v51, v0
	v_mov_b32_e32 v52, v0
	v_mov_b32_e32 v53, v0
	v_mov_b32_e32 v54, v0
	v_mov_b32_e32 v55, v0
	v_mov_b32_e32 v56, v0
	v_mov_b32_e32 v57, v0
	v_mov_b32_e32 v58, v0
	v_mov_b32_e32 v59, v0
	v_mov_b32_e32 v60, v0
	v_mov_b32_e32 v61, v0
	v_mov_b32_e32 v62, v0
	v_mov_b32_e32 v63, v0
	v_mov_b32_e32 v64, v0
	v_mov_b32_e32 v65, v0
	v_mov_b32_e32 v66, v0
	v_mov_b32_e32 v67, v0
	v_mov_b32_e32 v68, v0
	v_mov_b32_e32 v69, v0
	v_mov_b32_e32 v70, v0
	v_mov_b32_e32 v71, v0
	v_mov_b32_e32 v72, v0
	v_mov_b32_e32 v73, v0
	v_mov_b32_e32 v74, v0
	v_mov_b32_e32 v75, v0
	v_mov_b32_e32 v76, v0
	v_mov_b32_e32 v77, v0
	v_mov_b32_e32 v78, v0
	v_mov_b32_e32 v79, v0
	v_mov_b32_e32 v80, v0
	v_mov_b32_e32 v81, v0
	v_mov_b32_e32 v82, v0
	v_mov_b32_e32 v83, v0
	v_mov_b32_e32 v84, v0
	v_mov_b32_e32 v85, v0
	v_mov_b32_e32 v86, v0
	v_mov_b32_e32 v87, v0
	v_mov_b32_e32 v88, v0
	v_mov_b32_e32 v89, v0
	v_mov_b32_e32 v90, v0
	v_mov_b32_e32 v91, v0
	v_mov_b32_e32 v92, v0
	v_mov_b32_e32 v93, v0
	v_mov_b32_e32 v94, v0
	v_mov_b32_e32 v95, v0
	v_mov_b32_e32 v96, v0
	v_mov_b32_e32 v97, v0
	v_mov_b32_e32 v98, v0
	v_mov_b32_e32 v99, v0
	v_mov_b32_e32 v100, v0
	v_mov_b32_e32 v101, v0
	v_mov_b32_e32 v102, v0
	v_mov_b32_e32 v103, v0
	v_mov_b32_e32 v104, v0
	v_mov_b32_e32 v105, v0
	v_mov_b32_e32 v106, v0
	v_mov_b32_e32 v107, v0
	v_mov_b32_e32 v108, v0
	v_mov_b32_e32 v109, v0
	v_mov_b32_e32 v110, v0
	v_mov_b32_e32 v111, v0
	v_mov_b32_e32 v114, v0
	v_mov_b32_e32 v115, v0
	v_mov_b32_e32 v116, v0
	v_mov_b32_e32 v117, v0
	v_mov_b32_e32 v118, v0
	v_mov_b32_e32 v119, v0
	v_mov_b32_e32 v120, v0
	v_mov_b32_e32 v121, v0
	v_mov_b32_e32 v122, v0
	v_mov_b32_e32 v123, v0
	v_mov_b32_e32 v124, v0
	v_mov_b32_e32 v125, v0
	v_mov_b32_e32 v126, v0
	v_mov_b32_e32 v127, v0
	v_mov_b32_e32 v128, v0
	v_mov_b32_e32 v129, v0
	.p2align 6
	s_nop 0
	s_nop 0
	s_nop 0

.LBB0_862:
	s_ashr_i32 s15, s14, 31
	s_lshl_b64 s[16:17], s[14:15], 19
	s_add_u32 s16, s26, s16
	s_addc_u32 s17, s27, s17
	s_and_b64 s[18:19], s[2:3], exec
	s_cselect_b32 s15, s17, s23
	s_cselect_b32 s45, s16, s22
	s_ashr_i32 s9, s8, 31
	s_lshl_b64 s[18:19], s[8:9], 19
	s_add_u32 s18, s28, s18
	s_addc_u32 s19, s29, s19
	s_and_b64 s[24:25], s[2:3], exec
	s_cselect_b32 s9, s19, s21
	s_cselect_b32 s46, s18, s20
	s_add_u32 s47, s20, 0x100
	s_addc_u32 s48, s21, 0
	s_add_u32 s20, s22, 0x40080
	v_mov_b32_e32 v0, 0
	s_addc_u32 s21, s23, 0
	s_mov_b32 s49, -2
	v_mov_b32_e32 v1, v0
	v_mov_b32_e32 v2, v0
	v_mov_b32_e32 v3, v0
	v_mov_b32_e32 v4, v0
	v_mov_b32_e32 v5, v0
	v_mov_b32_e32 v6, v0
	v_mov_b32_e32 v7, v0
	v_mov_b32_e32 v8, v0
	v_mov_b32_e32 v9, v0
	v_mov_b32_e32 v10, v0
	v_mov_b32_e32 v11, v0
	v_mov_b32_e32 v12, v0
	v_mov_b32_e32 v13, v0
	v_mov_b32_e32 v14, v0
	v_mov_b32_e32 v15, v0
	v_mov_b32_e32 v16, v0
	v_mov_b32_e32 v17, v0
	v_mov_b32_e32 v18, v0
	v_mov_b32_e32 v19, v0
	v_mov_b32_e32 v20, v0
	v_mov_b32_e32 v21, v0
	v_mov_b32_e32 v22, v0
	v_mov_b32_e32 v23, v0
	v_mov_b32_e32 v24, v0
	v_mov_b32_e32 v25, v0
	v_mov_b32_e32 v26, v0
	v_mov_b32_e32 v27, v0
	v_mov_b32_e32 v28, v0
	v_mov_b32_e32 v29, v0
	v_mov_b32_e32 v30, v0
	v_mov_b32_e32 v31, v0
	v_mov_b32_e32 v72, v0
	v_mov_b32_e32 v73, v0
	v_mov_b32_e32 v74, v0
	v_mov_b32_e32 v75, v0
	v_mov_b32_e32 v76, v0
	v_mov_b32_e32 v77, v0
	v_mov_b32_e32 v78, v0
	v_mov_b32_e32 v79, v0
	v_mov_b32_e32 v80, v0
	v_mov_b32_e32 v81, v0
	v_mov_b32_e32 v82, v0
	v_mov_b32_e32 v83, v0
	v_mov_b32_e32 v84, v0
	v_mov_b32_e32 v85, v0
	v_mov_b32_e32 v86, v0
	v_mov_b32_e32 v87, v0
	v_mov_b32_e32 v88, v0
	v_mov_b32_e32 v89, v0
	v_mov_b32_e32 v90, v0
	v_mov_b32_e32 v91, v0
	v_mov_b32_e32 v92, v0
	v_mov_b32_e32 v93, v0
	v_mov_b32_e32 v94, v0
	v_mov_b32_e32 v95, v0
	v_mov_b32_e32 v96, v0
	v_mov_b32_e32 v97, v0
	v_mov_b32_e32 v98, v0
	v_mov_b32_e32 v99, v0
	v_mov_b32_e32 v100, v0
	v_mov_b32_e32 v101, v0
	v_mov_b32_e32 v102, v0
	v_mov_b32_e32 v103, v0
	v_mov_b32_e32 v32, v0
	v_mov_b32_e32 v33, v0
	v_mov_b32_e32 v34, v0
	v_mov_b32_e32 v35, v0
	v_mov_b32_e32 v36, v0
	v_mov_b32_e32 v37, v0
	v_mov_b32_e32 v38, v0
	v_mov_b32_e32 v39, v0
	v_mov_b32_e32 v40, v0
	v_mov_b32_e32 v41, v0
	v_mov_b32_e32 v42, v0
	v_mov_b32_e32 v43, v0
	v_mov_b32_e32 v44, v0
	v_mov_b32_e32 v45, v0
	v_mov_b32_e32 v46, v0
	v_mov_b32_e32 v47, v0
	v_mov_b32_e32 v56, v0
	v_mov_b32_e32 v57, v0
	v_mov_b32_e32 v58, v0
	v_mov_b32_e32 v59, v0
	v_mov_b32_e32 v60, v0
	v_mov_b32_e32 v61, v0
	v_mov_b32_e32 v62, v0
	v_mov_b32_e32 v63, v0
	v_mov_b32_e32 v64, v0
	v_mov_b32_e32 v65, v0
	v_mov_b32_e32 v66, v0
	v_mov_b32_e32 v67, v0
	v_mov_b32_e32 v68, v0
	v_mov_b32_e32 v69, v0
	v_mov_b32_e32 v70, v0
	v_mov_b32_e32 v71, v0
	v_mov_b32_e32 v104, v0
	v_mov_b32_e32 v105, v0
	v_mov_b32_e32 v106, v0
	v_mov_b32_e32 v107, v0
	v_mov_b32_e32 v108, v0
	v_mov_b32_e32 v109, v0
	v_mov_b32_e32 v110, v0
	v_mov_b32_e32 v111, v0
	v_mov_b32_e32 v114, v0
	v_mov_b32_e32 v115, v0
	v_mov_b32_e32 v116, v0
	v_mov_b32_e32 v117, v0
	v_mov_b32_e32 v118, v0
	v_mov_b32_e32 v119, v0
	v_mov_b32_e32 v120, v0
	v_mov_b32_e32 v121, v0
	v_mov_b32_e32 v130, v0
	v_mov_b32_e32 v131, v0
	v_mov_b32_e32 v132, v0
	v_mov_b32_e32 v133, v0
	v_mov_b32_e32 v134, v0
	v_mov_b32_e32 v135, v0
	v_mov_b32_e32 v136, v0
	v_mov_b32_e32 v137, v0
	v_mov_b32_e32 v138, v0
	v_mov_b32_e32 v139, v0
	v_mov_b32_e32 v140, v0
	v_mov_b32_e32 v141, v0
	v_mov_b32_e32 v142, v0
	v_mov_b32_e32 v143, v0
	v_mov_b32_e32 v144, v0
	v_mov_b32_e32 v145, v0
	.p2align 6
	s_nop 0
	s_nop 0
	s_nop 0
